# ten grid barriers (0-4, 6-10) split, one weight-transpose round per barrier between arrive and wait
# baseline (speedup 1.0000x reference)
.LBB0_126:
	s_cmp_lt_i32 s88, 1
	s_cbranch_scc0 .Lsl0_out
	s_cmp_gt_i32 s89, 0
	s_cbranch_scc0 .Lsl0_out
	s_load_dword s4, s[0:1], 0x120
	s_load_dwordx16 s[52:67], s[0:1], 0x0
	s_load_dwordx16 s[68:83], s[0:1], 0x80
	s_waitcnt lgkmcnt(0)
	s_lshl_b32 s4, s4, 1
	s_mul_i32 s5, s4, 1
	s_lshl_b32 s33, s2, 1
	s_add_i32 s33, s33, s5
	s_cmp_eq_u32 s89, 18
	s_cselect_b32 s5, 2, 11
	s_mul_i32 s4, s4, s5
	s_min_u32 s4, s4, 0x15d0
	s_cmp_ge_i32 s33, s4
	s_cbranch_scc1 .Lsl0_out
	s_add_u32 s94, s34, 0x1da0000
	s_addc_u32 s95, s35, 0
	v_writelane_b32 v252, s90, 0
	s_add_u32 s4, s34, 0x7a0000
	s_addc_u32 s5, s35, 0
	v_writelane_b32 v252, s91, 1
	v_writelane_b32 v252, s4, 2
	v_lshrrev_b32_e32 v138, 8, v204
	v_and_b32_e32 v139, 0xff, v204
	v_writelane_b32 v252, s5, 3
	s_add_u32 s4, s34, 0x720000
	s_addc_u32 s5, s35, 0
	v_writelane_b32 v252, s4, 4
	v_mul_u32_u24_e32 v140, 0x12000, v138
	v_mov_b32_e32 v129, 0
	v_writelane_b32 v252, s5, 5
	s_add_u32 s4, s34, 0x520000
	s_addc_u32 s5, s35, 0
	s_add_u32 s90, s34, 0x4a0000
	s_addc_u32 s91, s35, 0
	s_add_u32 s96, s34, 0x440000
	s_addc_u32 s97, s35, 0
	s_add_u32 s16, s34, 0x28a0000
	s_addc_u32 s17, s35, 0
	s_add_u32 s18, s0, 0x120
	v_writelane_b32 v252, s4, 6
	s_addc_u32 s19, s1, 0
	s_movk_i32 s8, 0x104
	s_movk_i32 s9, 0xffe0
	s_movk_i32 s10, 0x6000
	s_movk_i32 s11, 0x400
	s_mov_b32 s12, 0xbfb8aa3b
	s_mov_b32 s13, 0x42ce8ed0
	s_mov_b32 s14, 0xc2b17218
	s_movk_i32 s15, 0x1800
	v_mov_b32_e32 v141, 0xfffffd40
	v_mov_b32_e32 v142, 0xb00000
	v_mov_b32_e32 v143, 0x580000
	v_mov_b32_e32 v144, 0x7f800000
	v_writelane_b32 v252, s5, 7
	s_branch .Lsl0_22

.Lsl0_21:
	s_or_b64 exec, exec, s[20:21]
	s_waitcnt lgkmcnt(0)
	s_load_dword s4, s[18:19], 0x0
	s_waitcnt lgkmcnt(0)
	s_lshl_b32 s4, s4, 1
	s_add_i32 s33, s4, s33
	s_cmp_eq_u32 s89, 18
	s_cselect_b32 s5, 2, 11
	s_mul_i32 s4, s4, s5
	s_min_u32 s4, s4, 0x15d0
	s_cmp_lt_i32 s33, s4
	s_cbranch_scc0 .Lsl0_71

.LBB0_189:
	s_cmp_lg_u32 s88, 0
	s_cbranch_scc1 .Lsl1_out
	s_cmp_lg_u32 s89, 18
	s_cbranch_scc1 .Lsl1_out
	s_load_dword s4, s[0:1], 0x120
	s_load_dwordx16 s[52:67], s[0:1], 0x0
	s_load_dwordx16 s[68:83], s[0:1], 0x80
	s_waitcnt lgkmcnt(0)
	s_lshl_b32 s4, s4, 1
	s_mul_i32 s5, s4, 2
	s_lshl_b32 s33, s2, 1
	s_add_i32 s33, s33, s5
	s_mov_b32 s5, 3
	s_mul_i32 s4, s4, s5
	s_min_u32 s4, s4, 0x15d0
	s_cmp_ge_i32 s33, s4
	s_cbranch_scc1 .Lsl1_out
	s_add_u32 s94, s34, 0x1da0000
	s_addc_u32 s95, s35, 0
	v_writelane_b32 v252, s90, 0
	s_add_u32 s4, s34, 0x7a0000
	s_addc_u32 s5, s35, 0
	v_writelane_b32 v252, s91, 1
	v_writelane_b32 v252, s4, 2
	v_lshrrev_b32_e32 v138, 8, v204
	v_and_b32_e32 v139, 0xff, v204
	v_writelane_b32 v252, s5, 3
	s_add_u32 s4, s34, 0x720000
	s_addc_u32 s5, s35, 0
	v_writelane_b32 v252, s4, 4
	v_mul_u32_u24_e32 v140, 0x12000, v138
	v_mov_b32_e32 v129, 0
	v_writelane_b32 v252, s5, 5
	s_add_u32 s4, s34, 0x520000
	s_addc_u32 s5, s35, 0
	s_add_u32 s90, s34, 0x4a0000
	s_addc_u32 s91, s35, 0
	s_add_u32 s96, s34, 0x440000
	s_addc_u32 s97, s35, 0
	s_add_u32 s16, s34, 0x28a0000
	s_addc_u32 s17, s35, 0
	s_add_u32 s18, s0, 0x120
	v_writelane_b32 v252, s4, 6
	s_addc_u32 s19, s1, 0
	s_movk_i32 s8, 0x104
	s_movk_i32 s9, 0xffe0
	s_movk_i32 s10, 0x6000
	s_movk_i32 s11, 0x400
	s_mov_b32 s12, 0xbfb8aa3b
	s_mov_b32 s13, 0x42ce8ed0
	s_mov_b32 s14, 0xc2b17218
	s_movk_i32 s15, 0x1800
	v_mov_b32_e32 v141, 0xfffffd40
	v_mov_b32_e32 v142, 0xb00000
	v_mov_b32_e32 v143, 0x580000
	v_mov_b32_e32 v144, 0x7f800000
	v_writelane_b32 v252, s5, 7
	s_branch .Lsl1_22

.Lsl1_21:
	s_or_b64 exec, exec, s[20:21]
	s_waitcnt lgkmcnt(0)
	s_load_dword s4, s[18:19], 0x0
	s_waitcnt lgkmcnt(0)
	s_lshl_b32 s4, s4, 1
	s_add_i32 s33, s4, s33
	s_mov_b32 s5, 3
	s_mul_i32 s4, s4, s5
	s_min_u32 s4, s4, 0x15d0
	s_cmp_lt_i32 s33, s4
	s_cbranch_scc0 .Lsl1_71

.LBB0_1013:
	s_or_b64 exec, exec, s[4:5]
	s_waitcnt lgkmcnt(0)
	s_barrier
.LBB0_1014:
	s_cmp_lg_u32 s88, 0
	s_cbranch_scc1 .Lsl6_out
	s_cmp_lg_u32 s89, 18
	s_cbranch_scc1 .Lsl6_out
	s_load_dword s4, s[0:1], 0x120
	s_load_dwordx16 s[52:67], s[0:1], 0x0
	s_load_dwordx16 s[68:83], s[0:1], 0x80
	s_waitcnt lgkmcnt(0)
	s_lshl_b32 s4, s4, 1
	s_mul_i32 s5, s4, 6
	s_lshl_b32 s33, s2, 1
	s_add_i32 s33, s33, s5
	s_mov_b32 s5, 7
	s_mul_i32 s4, s4, s5
	s_min_u32 s4, s4, 0x15d0
	s_cmp_ge_i32 s33, s4
	s_cbranch_scc1 .Lsl6_out
	s_add_u32 s94, s34, 0x1da0000
	s_addc_u32 s95, s35, 0
	v_writelane_b32 v252, s90, 0
	s_add_u32 s4, s34, 0x7a0000
	s_addc_u32 s5, s35, 0
	v_writelane_b32 v252, s91, 1
	v_writelane_b32 v252, s4, 2
	v_lshrrev_b32_e32 v138, 8, v204
	v_and_b32_e32 v139, 0xff, v204
	v_writelane_b32 v252, s5, 3
	s_add_u32 s4, s34, 0x720000
	s_addc_u32 s5, s35, 0
	v_writelane_b32 v252, s4, 4
	v_mul_u32_u24_e32 v140, 0x12000, v138
	v_mov_b32_e32 v129, 0
	v_writelane_b32 v252, s5, 5
	s_add_u32 s4, s34, 0x520000
	s_addc_u32 s5, s35, 0
	s_add_u32 s90, s34, 0x4a0000
	s_addc_u32 s91, s35, 0
	s_add_u32 s96, s34, 0x440000
	s_addc_u32 s97, s35, 0
	s_add_u32 s16, s34, 0x28a0000
	s_addc_u32 s17, s35, 0
	s_add_u32 s18, s0, 0x120
	v_writelane_b32 v252, s4, 6
	s_addc_u32 s19, s1, 0
	s_movk_i32 s8, 0x104
	s_movk_i32 s9, 0xffe0
	s_movk_i32 s10, 0x6000
	s_movk_i32 s11, 0x400
	s_mov_b32 s12, 0xbfb8aa3b
	s_mov_b32 s13, 0x42ce8ed0
	s_mov_b32 s14, 0xc2b17218
	s_movk_i32 s15, 0x1800
	v_mov_b32_e32 v141, 0xfffffd40
	v_mov_b32_e32 v142, 0xb00000
	v_mov_b32_e32 v143, 0x580000
	v_mov_b32_e32 v144, 0x7f800000
	v_writelane_b32 v252, s5, 7
	s_branch .Lsl6_22

.Lsl10_out:
	s_cmp_gt_i32 s88, 10
	s_cbranch_scc1 .Lsb10_skip
	s_cmp_lt_i32 s89, 12
	s_cbranch_scc1 .Lsb10_skip
	s_waitcnt vmcnt(0) lgkmcnt(0)
	s_and_saveexec_b64 s[16:17], s[92:93]
	s_cbranch_execz .Lsb10_done
	v_mov_b32_e32 v0, 0x24008
	ds_read_b32 v1, v0
	buffer_inv sc1
	s_add_u32 s18, s34, 0xed10500
	s_addc_u32 s19, s35, 0
	v_mov_b32_e32 v0, 0
	s_mov_b32 s20, 0
	s_waitcnt lgkmcnt(0)

.Lsb10_skip:
	s_load_dwordx16 s[36:51], s[0:1], 0xc0
	s_cmp_gt_i32 s89, 11
	s_cselect_b64 s[6:7], -1, 0
	s_waitcnt lgkmcnt(0)
	s_cmp_lt_i32 s88, 12
	s_cselect_b64 s[4:5], -1, 0
	s_and_b64 s[6:7], s[4:5], s[6:7]
	s_andn2_b64 vcc, exec, s[6:7]
	s_cbranch_vccnz .LBB0_1270
	s_waitcnt vmcnt(7)
	v_lshl_add_u32 v0, s2, 3, v205
	s_movk_i32 s6, 0x2000
	v_cmp_gt_i32_e32 vcc, s6, v0
	s_and_saveexec_b64 s[6:7], vcc
	s_cbranch_execz .LBB0_1269
	v_lshlrev_b32_e32 v1, 2, v204
	s_waitcnt vmcnt(2)
	v_and_b32_e32 v22, 0xfc, v1
	v_mbcnt_lo_u32_b32 v1, -1, 0
	v_mov_b32_e32 v3, 0
	v_lshlrev_b32_e32 v2, 1, v22
	v_mbcnt_hi_u32_b32 v1, -1, v1
	v_lshl_add_u64 v[20:21], s[34:35], 0, v[2:3]
	v_and_b32_e32 v2, 64, v1
	v_add_u32_e32 v2, 64, v2
	v_xor_b32_e32 v8, 32, v1
	v_cmp_lt_i32_e32 vcc, v8, v2
	s_load_dwordx16 s[12:27], s[0:1], 0x40
	s_add_u32 s8, s34, 0x28b2000
	v_cndmask_b32_e32 v8, v1, v8, vcc
	v_lshlrev_b32_e32 v36, 2, v8
	v_xor_b32_e32 v8, 16, v1
	v_cmp_lt_i32_e32 vcc, v8, v2
	s_waitcnt lgkmcnt(0)
	s_mov_b64 s[12:13], s[16:17]
	s_addc_u32 s9, s35, 0
	v_cndmask_b32_e32 v8, v1, v8, vcc
	v_lshlrev_b32_e32 v37, 2, v8
	v_xor_b32_e32 v8, 8, v1
	v_cmp_lt_i32_e32 vcc, v8, v2
	s_mov_b64 s[14:15], s[18:19]
	s_add_u32 s12, s12, 0x1000
	v_cndmask_b32_e32 v8, v1, v8, vcc
	v_lshlrev_b32_e32 v38, 2, v8
	v_xor_b32_e32 v8, 4, v1
	v_cmp_lt_i32_e32 vcc, v8, v2
	s_mov_b64 s[14:15], 0x6a44000
	s_mov_b64 s[16:17], s[20:21]
	v_cndmask_b32_e32 v8, v1, v8, vcc
	v_lshlrev_b32_e32 v39, 2, v8
	v_xor_b32_e32 v8, 2, v1
	v_cmp_lt_i32_e32 vcc, v8, v2
	s_mov_b64 s[18:19], s[22:23]
	s_addc_u32 s13, s13, 0
	v_cndmask_b32_e32 v8, v1, v8, vcc
	v_lshlrev_b32_e32 v40, 2, v8
	v_xor_b32_e32 v8, 1, v1
	v_lshl_add_u64 v[4:5], v[20:21], 0, s[14:15]
	s_mov_b64 s[14:15], 0x7a44000
	v_cmp_lt_i32_e32 vcc, v8, v2
	v_lshlrev_b32_e32 v2, 2, v22
	s_waitcnt vmcnt(1)
	v_or_b32_e32 v24, 0x100, v22
	v_lshl_add_u64 v[6:7], v[20:21], 0, s[14:15]
	s_load_dword s14, s[0:1], 0x120
	v_cndmask_b32_e32 v1, v1, v8, vcc
	v_lshl_add_u64 v[8:9], s[12:13], 0, v[2:3]
	v_lshl_add_u64 v[10:11], s[18:19], 0, v[2:3]
	v_or_b32_e32 v26, 0x200, v22
	v_lshlrev_b32_e32 v2, 2, v24
	s_waitcnt vmcnt(0)
	v_or_b32_e32 v28, 0x300, v22
	v_lshl_add_u64 v[12:13], s[12:13], 0, v[2:3]
	v_lshlrev_b32_e32 v2, 2, v26
	v_lshl_add_u64 v[14:15], s[12:13], 0, v[2:3]
	v_lshlrev_b32_e32 v2, 2, v28
	v_lshl_add_u64 v[16:17], s[12:13], 0, v[2:3]
	s_mov_b64 s[12:13], 0xed11000
	v_lshl_add_u64 v[18:19], v[20:21], 0, s[12:13]
	s_mov_b64 s[12:13], 0x8a44000
	s_mov_b64 s[10:11], 0x1000
	v_lshlrev_b32_e32 v41, 2, v1
	s_waitcnt lgkmcnt(0)
	s_lshl_b32 s14, s14, 3
	v_lshl_add_u64 v[20:21], v[20:21], 0, s[12:13]
	s_mov_b64 s[12:13], 0
	s_movk_i32 s15, 0x1800
	s_movk_i32 s18, 0xfff
	s_mov_b64 s[16:17], 0x28a5000
	v_lshlrev_b32_e32 v2, 2, v22
	v_lshlrev_b32_e32 v22, 2, v24
	v_mov_b32_e32 v23, v3
	v_lshlrev_b32_e32 v24, 2, v26
	v_mov_b32_e32 v25, v3
	v_lshlrev_b32_e32 v26, 2, v28
	v_mov_b32_e32 v27, v3
	v_mov_b32_e32 v42, 0x358637bd
	s_mov_b32 s19, 0x800000
	s_movk_i32 s20, 0x1fff
